# v29 + per-unit vmcnt(0) drain in front of the K-loop removed (counted waits inside the loop already cover the prefetched tiles)
# speedup vs baseline: 1.0105x; 1.0038x over previous
; #define PG8_STAGE(bufoff, gbase, voff) do { _Pragma("unroll") for (int _i = 0; _i < 2; ++_i) \
;         __builtin_amdgcn_global_load_lds((const unsigned*)((const char*)(gbase) + (voff)[_i]), (PG8_LAS unsigned*)(lds + (bufoff) + ldsw + _i * 8192), 16, 0, 0); } while (0)
; #define PG8_LDA(dst, b, h) do { _Pragma("unroll") for (int m = 0; m < 4; ++m) _Pragma("unroll") for (int k = 0; k < 2; ++k) dst[m][k] = *(const PG8_LAS bf16x8*)(lds + PG8_SA(b, h) + aoff + m * 2048 + k * 1024); } while (0)
; #define PG8_LDB(dst, b, h) do { _Pragma("unroll") for (int n = 0; n < 2; ++n) _Pragma("unroll") for (int k = 0; k < 2; ++k) dst[n][k] = *(const PG8_LAS bf16x8*)(lds + PG8_SB(b, h) + boff + n * 2048 + k * 1024); } while (0)
; #define PG8_SCHED __builtin_amdgcn_sched_barrier(0)
; template <class Epi, class Sched, bool ALIGN_EPI = false, bool SP2 = false, bool F16 = false>
; __device__ __forceinline__ void gemm_phase(PG8_LAS unsigned char* lds, const Gemm g, const Sched& S, const Epi& E) {
;     ...
;     for (;;) {
;         const bool has_next = S.next(ui + 1, nxt);
;         const char* nA = has_next ? (const char*)g.A + (size_t)nxt.pm * tstepA : cA; const char* nB = has_next ? (const char*)g.Bt + (size_t)nxt.pn * tstepB : cB;
;         for (int t = 0; t < nt; t += 2) {
;             const bool last = (t == nt - 2);
;             const char* a1 = cA + (size_t)(t + 1) * kstep;
;             const char* a2 = last ? nA : cA + (size_t)(t + 2) * kstep; const char* b2 = last ? nB : cB + (size_t)(t + 2) * kstep;
;             const char* a3 = a2 + kstep; const char* b3 = b2 + kstep;
;             if (last && has_next) S.a_ready(nxt);
;             if constexpr (SP2) {
;             PG8_LDB(B0, 0, 0); PG8_LDB(B1, 0, 1); PG8_SCHED; PG8_LDA(At, 0, 0); PG8_STAGE(PG8_SA(1, 1), a1 + hstepA, voffA);
.LBB0_308:
	s_andn2_b64 vcc, exec, s[4:5]
	s_cbranch_vccnz .Lzk_gu
	s_add_u32 s52, s52, 0x80
	s_addc_u32 s53, s53, 0
	s_add_u32 s80, s54, 0x100
	s_addc_u32 s81, s55, 0
	s_mov_b32 s54, 0
	v_add_u32_e32 v139, 0x10000, v165
	v_add_u32_e32 v141, 0x14000, v165
	v_add_u32_e32 v143, 0x18000, v165
	v_add_u32_e32 v145, 0x1c000, v165

; #define PG8_STAGE(bufoff, gbase, voff) do { _Pragma("unroll") for (int _i = 0; _i < 2; ++_i) \
;         __builtin_amdgcn_global_load_lds((const unsigned*)((const char*)(gbase) + (voff)[_i]), (PG8_LAS unsigned*)(lds + (bufoff) + ldsw + _i * 8192), 16, 0, 0); } while (0)
; #define PG8_LDA(dst, b, h) do { _Pragma("unroll") for (int m = 0; m < 4; ++m) _Pragma("unroll") for (int k = 0; k < 2; ++k) dst[m][k] = *(const PG8_LAS bf16x8*)(lds + PG8_SA(b, h) + aoff + m * 2048 + k * 1024); } while (0)
; #define PG8_LDB(dst, b, h) do { _Pragma("unroll") for (int n = 0; n < 2; ++n) _Pragma("unroll") for (int k = 0; k < 2; ++k) dst[n][k] = *(const PG8_LAS bf16x8*)(lds + PG8_SB(b, h) + boff + n * 2048 + k * 1024); } while (0)
; #define PG8_SCHED __builtin_amdgcn_sched_barrier(0)
; template <class Epi, class Sched, bool ALIGN_EPI = false, bool SP2 = false, bool F16 = false>
; __device__ __forceinline__ void gemm_phase(PG8_LAS unsigned char* lds, const Gemm g, const Sched& S, const Epi& E) {
;     ...
;     for (;;) {
;         const bool has_next = S.next(ui + 1, nxt);
;         const char* nA = has_next ? (const char*)g.A + (size_t)nxt.pm * tstepA : cA; const char* nB = has_next ? (const char*)g.Bt + (size_t)nxt.pn * tstepB : cB;
;         for (int t = 0; t < nt; t += 2) {
;             const bool last = (t == nt - 2);
;             const char* a1 = cA + (size_t)(t + 1) * kstep;
;             const char* a2 = last ? nA : cA + (size_t)(t + 2) * kstep; const char* b2 = last ? nB : cB + (size_t)(t + 2) * kstep;
;             const char* a3 = a2 + kstep; const char* b3 = b2 + kstep;
;             if (last && has_next) S.a_ready(nxt);
;             if constexpr (SP2) {
;             PG8_LDB(B0, 0, 0); PG8_LDB(B1, 0, 1); PG8_SCHED; PG8_LDA(At, 0, 0); PG8_STAGE(PG8_SA(1, 1), a1 + hstepA, voffA);
.LBB0_343:
	s_andn2_b64 vcc, exec, s[4:5]
	s_cbranch_vccnz .Lzk_rs
	s_add_u32 s52, s52, 0x80
	s_addc_u32 s53, s53, 0
	s_add_u32 s79, s54, 0x100
	s_addc_u32 s80, s55, 0
	s_mov_b32 s54, 0
	v_add_u32_e32 v139, 0x10000, v158
	v_add_u32_e32 v141, 0x14000, v158
	v_add_u32_e32 v143, 0x18000, v158
	v_add_u32_e32 v157, 0x1c000, v158

; #define PG8_STAGE(bufoff, gbase, voff) do { _Pragma("unroll") for (int _i = 0; _i < 2; ++_i) \
;         __builtin_amdgcn_global_load_lds((const unsigned*)((const char*)(gbase) + (voff)[_i]), (PG8_LAS unsigned*)(lds + (bufoff) + ldsw + _i * 8192), 16, 0, 0); } while (0)
; #define PG8_LDA(dst, b, h) do { _Pragma("unroll") for (int m = 0; m < 4; ++m) _Pragma("unroll") for (int k = 0; k < 2; ++k) dst[m][k] = *(const PG8_LAS bf16x8*)(lds + PG8_SA(b, h) + aoff + m * 2048 + k * 1024); } while (0)
; #define PG8_LDB(dst, b, h) do { _Pragma("unroll") for (int n = 0; n < 2; ++n) _Pragma("unroll") for (int k = 0; k < 2; ++k) dst[n][k] = *(const PG8_LAS bf16x8*)(lds + PG8_SB(b, h) + boff + n * 2048 + k * 1024); } while (0)
; #define PG8_SCHED __builtin_amdgcn_sched_barrier(0)
; template <class Epi, class Sched, bool ALIGN_EPI = false, bool SP2 = false, bool F16 = false>
; __device__ __forceinline__ void gemm_phase(PG8_LAS unsigned char* lds, const Gemm g, const Sched& S, const Epi& E) {
;     ...
;     for (;;) {
;         const bool has_next = S.next(ui + 1, nxt);
;         const char* nA = has_next ? (const char*)g.A + (size_t)nxt.pm * tstepA : cA; const char* nB = has_next ? (const char*)g.Bt + (size_t)nxt.pn * tstepB : cB;
;         for (int t = 0; t < nt; t += 2) {
;             const bool last = (t == nt - 2);
;             const char* a1 = cA + (size_t)(t + 1) * kstep;
;             const char* a2 = last ? nA : cA + (size_t)(t + 2) * kstep; const char* b2 = last ? nB : cB + (size_t)(t + 2) * kstep;
;             const char* a3 = a2 + kstep; const char* b3 = b2 + kstep;
;             if (last && has_next) S.a_ready(nxt);
;             if constexpr (SP2) {
;             PG8_LDB(B0, 0, 0); PG8_LDB(B1, 0, 1); PG8_SCHED; PG8_LDA(At, 0, 0); PG8_STAGE(PG8_SA(1, 1), a1 + hstepA, voffA);
.LBB0_396:
	s_andn2_b64 vcc, exec, s[4:5]
	s_cbranch_vccnz .Lzk_bf
	s_add_u32 s46, s78, 0x80
	s_addc_u32 s47, s79, 0
	s_add_u32 s13, s72, 0x100
	s_addc_u32 s24, s73, 0
	s_mov_b32 s72, 0
	v_add_u32_e32 v155, 0x10000, v163
	v_add_u32_e32 v157, 0x14000, v163
	v_add_u32_e32 v159, 0x18000, v163
	v_add_u32_e32 v161, 0x1c000, v163

; #define PG8_STAGE(bufoff, gbase, voff) do { _Pragma("unroll") for (int _i = 0; _i < 2; ++_i) \
;         __builtin_amdgcn_global_load_lds((const unsigned*)((const char*)(gbase) + (voff)[_i]), (PG8_LAS unsigned*)(lds + (bufoff) + ldsw + _i * 8192), 16, 0, 0); } while (0)
; #define PG8_LDA(dst, b, h) do { _Pragma("unroll") for (int m = 0; m < 4; ++m) _Pragma("unroll") for (int k = 0; k < 2; ++k) dst[m][k] = *(const PG8_LAS bf16x8*)(lds + PG8_SA(b, h) + aoff + m * 2048 + k * 1024); } while (0)
; #define PG8_LDB(dst, b, h) do { _Pragma("unroll") for (int n = 0; n < 2; ++n) _Pragma("unroll") for (int k = 0; k < 2; ++k) dst[n][k] = *(const PG8_LAS bf16x8*)(lds + PG8_SB(b, h) + boff + n * 2048 + k * 1024); } while (0)
; #define PG8_SCHED __builtin_amdgcn_sched_barrier(0)
; template <class Epi, class Sched, bool ALIGN_EPI = false, bool SP2 = false, bool F16 = false>
; __device__ __forceinline__ void gemm_phase(PG8_LAS unsigned char* lds, const Gemm g, const Sched& S, const Epi& E) {
;     ...
;     for (;;) {
;         const bool has_next = S.next(ui + 1, nxt);
;         const char* nA = has_next ? (const char*)g.A + (size_t)nxt.pm * tstepA : cA; const char* nB = has_next ? (const char*)g.Bt + (size_t)nxt.pn * tstepB : cB;
;         for (int t = 0; t < nt; t += 2) {
;             const bool last = (t == nt - 2);
;             const char* a1 = cA + (size_t)(t + 1) * kstep;
;             const char* a2 = last ? nA : cA + (size_t)(t + 2) * kstep; const char* b2 = last ? nB : cB + (size_t)(t + 2) * kstep;
;             const char* a3 = a2 + kstep; const char* b3 = b2 + kstep;
;             if (last && has_next) S.a_ready(nxt);
;             if constexpr (SP2) {
;             PG8_LDB(B0, 0, 0); PG8_LDB(B1, 0, 1); PG8_SCHED; PG8_LDA(At, 0, 0); PG8_STAGE(PG8_SA(1, 1), a1 + hstepA, voffA);
.LBB0_562:
	s_andn2_b64 vcc, exec, s[4:5]
	s_cbranch_vccnz .Lzk_bh
	s_add_u32 s44, s72, 0x80
	s_addc_u32 s45, s73, 0
	s_add_u32 s24, s52, 0x100
	s_addc_u32 s72, s53, 0
	s_mov_b32 s52, 0
	v_add_u32_e32 v155, 0x10000, v163
	v_add_u32_e32 v157, 0x14000, v163
	v_add_u32_e32 v159, 0x18000, v163
	v_add_u32_e32 v161, 0x1c000, v163
